# conv: each chain pair's LayerNorm partial reduction is woven into the next pair's FMA stream (bpermute latency under FMAs)
# speedup vs baseline: 1.0071x; 1.0001x over previous
; DI void conv_item(const Params& p, char* lds, int t0, int tid) {
;     ...
;     float za[38], zb[38];
; #pragma unroll
;     for (int rr = 0; rr < 38; ++rr) {
;       const unsigned u = zl[(ps * 8 + rr) * 256 + tid];
;       za[rr] = __uint_as_float(u << 16); zb[rr] = __uint_as_float(u & 0xffff0000u);
;     }
;     float ya[8], yb[8];
; #pragma unroll
;     for (int i = 0; i < 8; ++i) {
;       float a = bias.x, b = bias.y;
; #pragma unroll
;       for (int j = 0; j < 31; ++j) { a += wa[j] * za[i + j]; b += wb[j] * zb[i + j]; }
.LBB0_196:
	ds_read2st64_b32 v[2:3], v238 offset1:4
	ds_read2st64_b32 v[4:5], v238 offset0:8 offset1:12
	ds_read2st64_b32 v[160:161], v238 offset0:40 offset1:44
	ds_read2st64_b32 v[170:171], v238 offset0:56 offset1:60
	ds_read2st64_b32 v[178:179], v238 offset0:72 offset1:76
	s_waitcnt lgkmcnt(4)
	v_lshlrev_b32_e32 v204, 16, v2
	v_and_b32_e32 v205, 0xffff0000, v2
	v_lshlrev_b32_e32 v156, 16, v3
	v_and_b32_e32 v157, 0xffff0000, v3
	ds_read2st64_b32 v[2:3], v238 offset0:16 offset1:20
	s_waitcnt lgkmcnt(4)
	v_lshlrev_b32_e32 v158, 16, v4
	v_and_b32_e32 v159, 0xffff0000, v4
	v_lshlrev_b32_e32 v164, 16, v5
	v_and_b32_e32 v165, 0xffff0000, v5
	s_waitcnt lgkmcnt(0)
	v_lshlrev_b32_e32 v148, 16, v2
	v_and_b32_e32 v149, 0xffff0000, v2
	v_lshlrev_b32_e32 v150, 16, v3
	v_and_b32_e32 v151, 0xffff0000, v3
	ds_read2st64_b32 v[2:3], v238 offset0:32 offset1:36
	ds_read2st64_b32 v[4:5], v238 offset0:24 offset1:28
	v_lshlrev_b32_e32 v154, 16, v160
	v_and_b32_e32 v155, 0xffff0000, v160
	v_lshlrev_b32_e32 v160, 16, v161
	s_waitcnt lgkmcnt(1)
	v_lshlrev_b32_e32 v6, 16, v2
	v_and_b32_e32 v7, 0xffff0000, v2
	v_lshlrev_b32_e32 v8, 16, v3
	v_and_b32_e32 v9, 0xffff0000, v3
	ds_read2st64_b32 v[2:3], v238 offset0:48 offset1:52
	s_waitcnt lgkmcnt(1)
	v_lshlrev_b32_e32 v152, 16, v4
	v_and_b32_e32 v153, 0xffff0000, v4
	v_lshlrev_b32_e32 v4, 16, v5
	v_and_b32_e32 v5, 0xffff0000, v5
	s_waitcnt lgkmcnt(0)
	v_lshlrev_b32_e32 v162, 16, v2
	v_and_b32_e32 v163, 0xffff0000, v2
	v_lshlrev_b32_e32 v166, 16, v3
	v_and_b32_e32 v167, 0xffff0000, v3
	ds_read2st64_b32 v[2:3], v238 offset0:64 offset1:68
	v_and_b32_e32 v161, 0xffff0000, v161
	v_lshlrev_b32_e32 v168, 16, v170
	v_and_b32_e32 v169, 0xffff0000, v170
	v_lshlrev_b32_e32 v170, 16, v171
	s_waitcnt lgkmcnt(0)
	v_lshlrev_b32_e32 v172, 16, v2
	v_and_b32_e32 v173, 0xffff0000, v2
	v_lshlrev_b32_e32 v174, 16, v3
	v_and_b32_e32 v175, 0xffff0000, v3
	ds_read2st64_b32 v[2:3], v238 offset0:80 offset1:84
	v_and_b32_e32 v171, 0xffff0000, v171
	ds_read2st64_b32 v[186:187], v238 offset0:88 offset1:92
	v_lshlrev_b32_e32 v176, 16, v178
	v_and_b32_e32 v177, 0xffff0000, v178
	s_waitcnt lgkmcnt(1)
	v_lshlrev_b32_e32 v180, 16, v2
	v_and_b32_e32 v181, 0xffff0000, v2
	v_lshlrev_b32_e32 v182, 16, v3
	v_and_b32_e32 v183, 0xffff0000, v3
	ds_read2st64_b32 v[2:3], v238 offset0:96 offset1:100
	v_lshlrev_b32_e32 v178, 16, v179
	v_and_b32_e32 v179, 0xffff0000, v179
	ds_read2st64_b32 v[194:195], v238 offset0:104 offset1:108
	s_waitcnt lgkmcnt(2)
	v_lshlrev_b32_e32 v184, 16, v186
	s_waitcnt lgkmcnt(1)
	v_lshlrev_b32_e32 v188, 16, v2
	v_and_b32_e32 v189, 0xffff0000, v2
	v_lshlrev_b32_e32 v190, 16, v3
	v_and_b32_e32 v191, 0xffff0000, v3
	ds_read2st64_b32 v[2:3], v238 offset0:112 offset1:116
	v_and_b32_e32 v185, 0xffff0000, v186
	v_lshlrev_b32_e32 v186, 16, v187
	v_and_b32_e32 v187, 0xffff0000, v187
	ds_read2st64_b32 v[202:203], v238 offset0:120 offset1:124
	s_waitcnt lgkmcnt(1)
	v_lshlrev_b32_e32 v196, 16, v2
	v_and_b32_e32 v197, 0xffff0000, v2
	v_lshlrev_b32_e32 v198, 16, v3
	v_and_b32_e32 v199, 0xffff0000, v3
	v_pk_fma_f32 v[2:3], v[122:123], v[204:205], v[128:129]
	v_lshlrev_b32_e32 v192, 16, v194
	v_pk_fma_f32 v[2:3], v[124:125], v[156:157], v[2:3]
	ds_read2st64_b32 v[208:209], v238 offset0:128 offset1:132
	ds_read2st64_b32 v[210:211], v238 offset0:136 offset1:140
	ds_read2st64_b32 v[204:205], v238 offset0:144 offset1:148
	v_pk_fma_f32 v[156:157], v[122:123], v[156:157], v[128:129]
	v_and_b32_e32 v193, 0xffff0000, v194
	v_pk_fma_f32 v[2:3], v[126:127], v[158:159], v[2:3]
	v_lshlrev_b32_e32 v194, 16, v195
	v_pk_fma_f32 v[2:3], v[120:121], v[164:165], v[2:3]
	v_and_b32_e32 v195, 0xffff0000, v195
	v_pk_fma_f32 v[2:3], v[80:81], v[148:149], v[2:3]
	s_waitcnt lgkmcnt(0)
	v_lshlrev_b32_e32 v200, 16, v202
	v_pk_fma_f32 v[2:3], v[82:83], v[150:151], v[2:3]
	v_and_b32_e32 v201, 0xffff0000, v202
	v_lshlrev_b32_e32 v202, 16, v203
	v_pk_fma_f32 v[156:157], v[124:125], v[158:159], v[156:157]
	v_pk_fma_f32 v[2:3], v[84:85], v[152:153], v[2:3]
	v_and_b32_e32 v203, 0xffff0000, v203
	v_pk_fma_f32 v[156:157], v[126:127], v[164:165], v[156:157]
	v_pk_fma_f32 v[2:3], v[86:87], v[4:5], v[2:3]
	v_pk_fma_f32 v[156:157], v[120:121], v[148:149], v[156:157]
	v_pk_fma_f32 v[2:3], v[88:89], v[6:7], v[2:3]
	v_pk_fma_f32 v[156:157], v[80:81], v[150:151], v[156:157]
	v_pk_fma_f32 v[2:3], v[90:91], v[8:9], v[2:3]
	v_pk_fma_f32 v[156:157], v[82:83], v[152:153], v[156:157]
	v_pk_fma_f32 v[2:3], v[92:93], v[154:155], v[2:3]
	v_pk_fma_f32 v[156:157], v[84:85], v[4:5], v[156:157]
	v_pk_fma_f32 v[2:3], v[94:95], v[160:161], v[2:3]
	v_pk_fma_f32 v[156:157], v[86:87], v[6:7], v[156:157]
	v_pk_fma_f32 v[2:3], v[96:97], v[162:163], v[2:3]
	v_pk_fma_f32 v[156:157], v[88:89], v[8:9], v[156:157]
	v_pk_fma_f32 v[2:3], v[98:99], v[166:167], v[2:3]
	v_pk_fma_f32 v[156:157], v[90:91], v[154:155], v[156:157]
	v_pk_fma_f32 v[2:3], v[100:101], v[168:169], v[2:3]
	v_pk_fma_f32 v[156:157], v[92:93], v[160:161], v[156:157]
	v_pk_fma_f32 v[2:3], v[102:103], v[170:171], v[2:3]
	v_pk_fma_f32 v[156:157], v[94:95], v[162:163], v[156:157]
	v_pk_fma_f32 v[2:3], v[104:105], v[172:173], v[2:3]
	v_pk_fma_f32 v[156:157], v[96:97], v[166:167], v[156:157]
	v_pk_fma_f32 v[2:3], v[106:107], v[174:175], v[2:3]
	v_pk_fma_f32 v[156:157], v[98:99], v[168:169], v[156:157]
	v_pk_fma_f32 v[2:3], v[108:109], v[176:177], v[2:3]
	v_pk_fma_f32 v[156:157], v[100:101], v[170:171], v[156:157]
	v_pk_fma_f32 v[2:3], v[110:111], v[178:179], v[2:3]
	v_pk_fma_f32 v[156:157], v[102:103], v[172:173], v[156:157]
	v_pk_fma_f32 v[2:3], v[112:113], v[180:181], v[2:3]
	v_pk_fma_f32 v[156:157], v[104:105], v[174:175], v[156:157]
; DI void conv_item(const Params& p, char* lds, int t0, int tid) {
;     ...
;     for (int i = 0; i < 8; ++i) {
;       float a = bias.x, b = bias.y;
; #pragma unroll
;       for (int j = 0; j < 31; ++j) { a += wa[j] * za[i + j]; b += wb[j] * zb[i + j]; }
;       ya[i] = a; yb[i] = b;
;     }
; #pragma unroll
;     for (int i = 0; i < 8; ++i) {
;       float s1 = wave_sum(ya[i] + yb[i]);
;       float s2 = wave_sum(ya[i] * ya[i] + yb[i] * yb[i]);
;       if (lane == 0) { red[(w * 8 + i) * 2] = s1; red[(w * 8 + i) * 2 + 1] = s2; }
;     }
	v_pk_fma_f32 v[2:3], v[114:115], v[182:183], v[2:3]
	v_pk_fma_f32 v[156:157], v[106:107], v[176:177], v[156:157]
	v_pk_fma_f32 v[2:3], v[116:117], v[184:185], v[2:3]
	v_pk_fma_f32 v[156:157], v[108:109], v[178:179], v[156:157]
	v_pk_fma_f32 v[2:3], v[118:119], v[186:187], v[2:3]
	v_pk_fma_f32 v[156:157], v[110:111], v[180:181], v[156:157]
	v_pk_fma_f32 v[2:3], v[130:131], v[188:189], v[2:3]
	v_pk_fma_f32 v[156:157], v[112:113], v[182:183], v[156:157]
	v_pk_fma_f32 v[2:3], v[132:133], v[190:191], v[2:3]
	v_pk_fma_f32 v[156:157], v[114:115], v[184:185], v[156:157]
	v_pk_fma_f32 v[2:3], v[134:135], v[192:193], v[2:3]
	v_pk_fma_f32 v[156:157], v[116:117], v[186:187], v[156:157]
	v_pk_fma_f32 v[2:3], v[136:137], v[194:195], v[2:3]
	v_pk_fma_f32 v[156:157], v[118:119], v[188:189], v[156:157]
	v_pk_fma_f32 v[2:3], v[138:139], v[196:197], v[2:3]
	v_pk_fma_f32 v[156:157], v[130:131], v[190:191], v[156:157]
	v_pk_fma_f32 v[2:3], v[140:141], v[198:199], v[2:3]
	v_pk_fma_f32 v[156:157], v[132:133], v[192:193], v[156:157]
	v_pk_fma_f32 v[2:3], v[142:143], v[200:201], v[2:3]
	v_pk_fma_f32 v[156:157], v[134:135], v[194:195], v[156:157]
	s_nop 0
	v_pk_fma_f32 v[156:157], v[136:137], v[196:197], v[156:157]
	s_nop 0
	v_pk_fma_f32 v[156:157], v[138:139], v[198:199], v[156:157]
	s_nop 0
	v_pk_fma_f32 v[156:157], v[140:141], v[200:201], v[156:157]
	s_nop 0
	v_pk_fma_f32 v[156:157], v[142:143], v[202:203], v[156:157]
	s_nop 0
	v_pk_mul_f32 v[250:251], v[2:3], v[2:3]
	v_pk_mul_f32 v[252:253], v[156:157], v[156:157]
	v_add_f32_e32 v240, v2, v3
	v_add_f32_e32 v244, v156, v157
	v_add_f32_e32 v241, v250, v251
	v_add_f32_e32 v245, v252, v253
	ds_bpermute_b32 v242, v222, v240
	ds_bpermute_b32 v243, v222, v241
	ds_bpermute_b32 v248, v222, v244
	ds_bpermute_b32 v249, v222, v245
	v_pk_fma_f32 v[158:159], v[122:123], v[158:159], v[128:129]
	v_lshlrev_b32_e32 v206, 16, v208
	v_pk_fma_f32 v[158:159], v[124:125], v[164:165], v[158:159]
	v_pk_fma_f32 v[164:165], v[122:123], v[164:165], v[128:129]
	v_and_b32_e32 v207, 0xffff0000, v208
	v_pk_fma_f32 v[158:159], v[126:127], v[148:149], v[158:159]
	v_lshlrev_b32_e32 v208, 16, v209
	v_pk_fma_f32 v[164:165], v[124:125], v[148:149], v[164:165]
	v_pk_fma_f32 v[158:159], v[120:121], v[150:151], v[158:159]
	v_and_b32_e32 v209, 0xffff0000, v209
	v_pk_fma_f32 v[164:165], v[126:127], v[150:151], v[164:165]
	v_pk_fma_f32 v[158:159], v[80:81], v[152:153], v[158:159]
	s_waitcnt lgkmcnt(2)
	v_pk_add_f32 v[240:241], v[240:241], v[242:243]
	s_waitcnt lgkmcnt(0)
	v_pk_add_f32 v[244:245], v[244:245], v[248:249]
	ds_bpermute_b32 v242, v223, v240
	ds_bpermute_b32 v243, v223, v241
	ds_bpermute_b32 v248, v223, v244
	ds_bpermute_b32 v249, v223, v245
	v_pk_fma_f32 v[164:165], v[120:121], v[152:153], v[164:165]
	v_pk_fma_f32 v[158:159], v[82:83], v[4:5], v[158:159]
	v_pk_fma_f32 v[164:165], v[80:81], v[4:5], v[164:165]
	v_pk_fma_f32 v[158:159], v[84:85], v[6:7], v[158:159]
	v_pk_fma_f32 v[164:165], v[82:83], v[6:7], v[164:165]
	v_pk_fma_f32 v[158:159], v[86:87], v[8:9], v[158:159]
	v_pk_fma_f32 v[164:165], v[84:85], v[8:9], v[164:165]
	v_pk_fma_f32 v[158:159], v[88:89], v[154:155], v[158:159]
	v_pk_fma_f32 v[164:165], v[86:87], v[154:155], v[164:165]
	v_pk_fma_f32 v[158:159], v[90:91], v[160:161], v[158:159]
	v_pk_fma_f32 v[164:165], v[88:89], v[160:161], v[164:165]
	v_pk_fma_f32 v[158:159], v[92:93], v[162:163], v[158:159]
	s_waitcnt lgkmcnt(2)
	v_pk_add_f32 v[240:241], v[240:241], v[242:243]
	s_waitcnt lgkmcnt(0)
	v_pk_add_f32 v[244:245], v[244:245], v[248:249]
	ds_bpermute_b32 v242, v224, v240
	ds_bpermute_b32 v243, v224, v241
	ds_bpermute_b32 v248, v224, v244
	ds_bpermute_b32 v249, v224, v245
	v_pk_fma_f32 v[164:165], v[90:91], v[162:163], v[164:165]
	v_pk_fma_f32 v[158:159], v[94:95], v[166:167], v[158:159]
	v_pk_fma_f32 v[164:165], v[92:93], v[166:167], v[164:165]
	v_pk_fma_f32 v[158:159], v[96:97], v[168:169], v[158:159]
	v_pk_fma_f32 v[164:165], v[94:95], v[168:169], v[164:165]
	v_pk_fma_f32 v[158:159], v[98:99], v[170:171], v[158:159]
	v_pk_fma_f32 v[164:165], v[96:97], v[170:171], v[164:165]
	v_pk_fma_f32 v[158:159], v[100:101], v[172:173], v[158:159]
	v_pk_fma_f32 v[164:165], v[98:99], v[172:173], v[164:165]
	v_pk_fma_f32 v[158:159], v[102:103], v[174:175], v[158:159]
	v_pk_fma_f32 v[164:165], v[100:101], v[174:175], v[164:165]
	v_pk_fma_f32 v[158:159], v[104:105], v[176:177], v[158:159]
	s_waitcnt lgkmcnt(2)
	v_pk_add_f32 v[240:241], v[240:241], v[242:243]
	s_waitcnt lgkmcnt(0)
	v_pk_add_f32 v[244:245], v[244:245], v[248:249]
	ds_bpermute_b32 v242, v225, v240
	ds_bpermute_b32 v243, v225, v241
	ds_bpermute_b32 v248, v225, v244
	ds_bpermute_b32 v249, v225, v245
	v_pk_fma_f32 v[164:165], v[102:103], v[176:177], v[164:165]
	v_pk_fma_f32 v[158:159], v[106:107], v[178:179], v[158:159]
	v_pk_fma_f32 v[164:165], v[104:105], v[178:179], v[164:165]
	v_pk_fma_f32 v[158:159], v[108:109], v[180:181], v[158:159]
	v_pk_fma_f32 v[164:165], v[106:107], v[180:181], v[164:165]
	v_pk_fma_f32 v[158:159], v[110:111], v[182:183], v[158:159]
	v_pk_fma_f32 v[164:165], v[108:109], v[182:183], v[164:165]
	v_pk_fma_f32 v[158:159], v[112:113], v[184:185], v[158:159]
	v_pk_fma_f32 v[164:165], v[110:111], v[184:185], v[164:165]
	v_pk_fma_f32 v[158:159], v[114:115], v[186:187], v[158:159]
	v_pk_fma_f32 v[164:165], v[112:113], v[186:187], v[164:165]
	v_pk_fma_f32 v[158:159], v[116:117], v[188:189], v[158:159]
	s_waitcnt lgkmcnt(2)
	v_pk_add_f32 v[240:241], v[240:241], v[242:243]
	s_waitcnt lgkmcnt(0)
; DI void conv_item(const Params& p, char* lds, int t0, int tid) {
;     ...
;     for (int i = 0; i < 8; ++i) {
;       float a = bias.x, b = bias.y;
; #pragma unroll
;       for (int j = 0; j < 31; ++j) { a += wa[j] * za[i + j]; b += wb[j] * zb[i + j]; }
;       ya[i] = a; yb[i] = b;
;     }
; #pragma unroll
;     for (int i = 0; i < 8; ++i) {
;       float s1 = wave_sum(ya[i] + yb[i]);
;       float s2 = wave_sum(ya[i] * ya[i] + yb[i] * yb[i]);
;       if (lane == 0) { red[(w * 8 + i) * 2] = s1; red[(w * 8 + i) * 2 + 1] = s2; }
;     }
	v_pk_add_f32 v[244:245], v[244:245], v[248:249]
	ds_bpermute_b32 v242, v226, v240
	ds_bpermute_b32 v243, v226, v241
	ds_bpermute_b32 v248, v226, v244
	ds_bpermute_b32 v249, v226, v245
	v_pk_fma_f32 v[164:165], v[114:115], v[188:189], v[164:165]
	v_pk_fma_f32 v[158:159], v[118:119], v[190:191], v[158:159]
	v_pk_fma_f32 v[164:165], v[116:117], v[190:191], v[164:165]
	v_pk_fma_f32 v[158:159], v[130:131], v[192:193], v[158:159]
	v_pk_fma_f32 v[164:165], v[118:119], v[192:193], v[164:165]
	v_pk_fma_f32 v[158:159], v[132:133], v[194:195], v[158:159]
	v_pk_fma_f32 v[164:165], v[130:131], v[194:195], v[164:165]
	v_pk_fma_f32 v[158:159], v[134:135], v[196:197], v[158:159]
	v_pk_fma_f32 v[164:165], v[132:133], v[196:197], v[164:165]
	v_pk_fma_f32 v[158:159], v[136:137], v[198:199], v[158:159]
	v_pk_fma_f32 v[164:165], v[134:135], v[198:199], v[164:165]
	v_pk_fma_f32 v[158:159], v[138:139], v[200:201], v[158:159]
	s_waitcnt lgkmcnt(2)
	v_pk_add_f32 v[240:241], v[240:241], v[242:243]
	s_waitcnt lgkmcnt(0)
	v_pk_add_f32 v[244:245], v[244:245], v[248:249]
	ds_bpermute_b32 v242, v227, v240
	ds_bpermute_b32 v243, v227, v241
	ds_bpermute_b32 v248, v227, v244
	ds_bpermute_b32 v249, v227, v245
	v_pk_fma_f32 v[164:165], v[136:137], v[200:201], v[164:165]
	v_pk_fma_f32 v[158:159], v[140:141], v[202:203], v[158:159]
	v_pk_fma_f32 v[164:165], v[138:139], v[202:203], v[164:165]
	v_pk_fma_f32 v[158:159], v[142:143], v[206:207], v[158:159]
	v_pk_fma_f32 v[164:165], v[140:141], v[206:207], v[164:165]
	s_nop 0
	v_pk_fma_f32 v[164:165], v[142:143], v[208:209], v[164:165]
	s_waitcnt lgkmcnt(2)
	v_pk_add_f32 v[240:241], v[240:241], v[242:243]
	s_waitcnt lgkmcnt(0)
	v_pk_add_f32 v[244:245], v[244:245], v[248:249]
	s_and_saveexec_b64 s[6:7], s[4:5]
	ds_write_b64 v228, v[240:241] offset:63488
	ds_write_b64 v228, v[244:245] offset:63496
	s_or_b64 exec, exec, s[6:7]
	s_nop 0
	v_pk_mul_f32 v[250:251], v[158:159], v[158:159]
	v_pk_mul_f32 v[252:253], v[164:165], v[164:165]
	v_add_f32_e32 v240, v158, v159
	v_add_f32_e32 v244, v164, v165
	v_add_f32_e32 v241, v250, v251
	v_add_f32_e32 v245, v252, v253
	ds_bpermute_b32 v242, v222, v240
	ds_bpermute_b32 v243, v222, v241
	ds_bpermute_b32 v248, v222, v244
	ds_bpermute_b32 v249, v222, v245
	v_pk_fma_f32 v[148:149], v[122:123], v[148:149], v[128:129]
	v_lshlrev_b32_e32 v212, 16, v210
	v_pk_fma_f32 v[148:149], v[124:125], v[150:151], v[148:149]
	v_pk_fma_f32 v[150:151], v[122:123], v[150:151], v[128:129]
	v_and_b32_e32 v213, 0xffff0000, v210
	v_pk_fma_f32 v[148:149], v[126:127], v[152:153], v[148:149]
	v_lshlrev_b32_e32 v210, 16, v211
	v_pk_fma_f32 v[150:151], v[124:125], v[152:153], v[150:151]
	v_pk_fma_f32 v[148:149], v[120:121], v[4:5], v[148:149]
	v_and_b32_e32 v211, 0xffff0000, v211
	v_pk_fma_f32 v[150:151], v[126:127], v[4:5], v[150:151]
	v_pk_fma_f32 v[148:149], v[80:81], v[6:7], v[148:149]
	s_waitcnt lgkmcnt(2)
	v_pk_add_f32 v[240:241], v[240:241], v[242:243]
	s_waitcnt lgkmcnt(0)
	v_pk_add_f32 v[244:245], v[244:245], v[248:249]
	ds_bpermute_b32 v242, v223, v240
	ds_bpermute_b32 v243, v223, v241
	ds_bpermute_b32 v248, v223, v244
	ds_bpermute_b32 v249, v223, v245
	v_pk_fma_f32 v[150:151], v[120:121], v[6:7], v[150:151]
	v_pk_fma_f32 v[148:149], v[82:83], v[8:9], v[148:149]
	v_pk_fma_f32 v[150:151], v[80:81], v[8:9], v[150:151]
	v_pk_fma_f32 v[148:149], v[84:85], v[154:155], v[148:149]
	v_pk_fma_f32 v[150:151], v[82:83], v[154:155], v[150:151]
	v_pk_fma_f32 v[148:149], v[86:87], v[160:161], v[148:149]
	v_pk_fma_f32 v[150:151], v[84:85], v[160:161], v[150:151]
	v_pk_fma_f32 v[148:149], v[88:89], v[162:163], v[148:149]
	v_pk_fma_f32 v[150:151], v[86:87], v[162:163], v[150:151]
	v_pk_fma_f32 v[148:149], v[90:91], v[166:167], v[148:149]
	v_pk_fma_f32 v[150:151], v[88:89], v[166:167], v[150:151]
	v_pk_fma_f32 v[148:149], v[92:93], v[168:169], v[148:149]
	s_waitcnt lgkmcnt(2)
	v_pk_add_f32 v[240:241], v[240:241], v[242:243]
	s_waitcnt lgkmcnt(0)
	v_pk_add_f32 v[244:245], v[244:245], v[248:249]
	ds_bpermute_b32 v242, v224, v240
	ds_bpermute_b32 v243, v224, v241
	ds_bpermute_b32 v248, v224, v244
	ds_bpermute_b32 v249, v224, v245
	v_pk_fma_f32 v[150:151], v[90:91], v[168:169], v[150:151]
	v_pk_fma_f32 v[148:149], v[94:95], v[170:171], v[148:149]
	v_pk_fma_f32 v[150:151], v[92:93], v[170:171], v[150:151]
	v_pk_fma_f32 v[148:149], v[96:97], v[172:173], v[148:149]
	v_pk_fma_f32 v[150:151], v[94:95], v[172:173], v[150:151]
	v_pk_fma_f32 v[148:149], v[98:99], v[174:175], v[148:149]
	v_pk_fma_f32 v[150:151], v[96:97], v[174:175], v[150:151]
	v_pk_fma_f32 v[148:149], v[100:101], v[176:177], v[148:149]
	v_pk_fma_f32 v[150:151], v[98:99], v[176:177], v[150:151]
	v_pk_fma_f32 v[148:149], v[102:103], v[178:179], v[148:149]
	v_pk_fma_f32 v[150:151], v[100:101], v[178:179], v[150:151]
	v_pk_fma_f32 v[148:149], v[104:105], v[180:181], v[148:149]
	s_waitcnt lgkmcnt(2)
	v_pk_add_f32 v[240:241], v[240:241], v[242:243]
	s_waitcnt lgkmcnt(0)
	v_pk_add_f32 v[244:245], v[244:245], v[248:249]
	ds_bpermute_b32 v242, v225, v240
	ds_bpermute_b32 v243, v225, v241
	ds_bpermute_b32 v248, v225, v244
	ds_bpermute_b32 v249, v225, v245
	v_pk_fma_f32 v[150:151], v[102:103], v[180:181], v[150:151]
	v_pk_fma_f32 v[148:149], v[106:107], v[182:183], v[148:149]
	v_pk_fma_f32 v[150:151], v[104:105], v[182:183], v[150:151]
	v_pk_fma_f32 v[148:149], v[108:109], v[184:185], v[148:149]
	v_pk_fma_f32 v[150:151], v[106:107], v[184:185], v[150:151]
	v_pk_fma_f32 v[148:149], v[110:111], v[186:187], v[148:149]
	v_pk_fma_f32 v[150:151], v[108:109], v[186:187], v[150:151]
	v_pk_fma_f32 v[148:149], v[112:113], v[188:189], v[148:149]
	v_pk_fma_f32 v[150:151], v[110:111], v[188:189], v[150:151]
	v_pk_fma_f32 v[148:149], v[114:115], v[190:191], v[148:149]
	v_pk_fma_f32 v[150:151], v[112:113], v[190:191], v[150:151]
	v_pk_fma_f32 v[148:149], v[116:117], v[192:193], v[148:149]
	s_waitcnt lgkmcnt(2)
; DI void conv_item(const Params& p, char* lds, int t0, int tid) {
;     ...
;     for (int i = 0; i < 8; ++i) {
;       float a = bias.x, b = bias.y;
; #pragma unroll
;       for (int j = 0; j < 31; ++j) { a += wa[j] * za[i + j]; b += wb[j] * zb[i + j]; }
;       ya[i] = a; yb[i] = b;
;     }
; #pragma unroll
;     for (int i = 0; i < 8; ++i) {
;       float s1 = wave_sum(ya[i] + yb[i]);
;       float s2 = wave_sum(ya[i] * ya[i] + yb[i] * yb[i]);
;       if (lane == 0) { red[(w * 8 + i) * 2] = s1; red[(w * 8 + i) * 2 + 1] = s2; }
;     }
	v_pk_add_f32 v[240:241], v[240:241], v[242:243]
	s_waitcnt lgkmcnt(0)
	v_pk_add_f32 v[244:245], v[244:245], v[248:249]
	ds_bpermute_b32 v242, v226, v240
	ds_bpermute_b32 v243, v226, v241
	ds_bpermute_b32 v248, v226, v244
	ds_bpermute_b32 v249, v226, v245
	v_pk_fma_f32 v[150:151], v[114:115], v[192:193], v[150:151]
	v_pk_fma_f32 v[148:149], v[118:119], v[194:195], v[148:149]
	v_pk_fma_f32 v[150:151], v[116:117], v[194:195], v[150:151]
	v_pk_fma_f32 v[148:149], v[130:131], v[196:197], v[148:149]
	v_pk_fma_f32 v[150:151], v[118:119], v[196:197], v[150:151]
	v_pk_fma_f32 v[148:149], v[132:133], v[198:199], v[148:149]
	v_pk_fma_f32 v[150:151], v[130:131], v[198:199], v[150:151]
	v_pk_fma_f32 v[148:149], v[134:135], v[200:201], v[148:149]
	v_pk_fma_f32 v[150:151], v[132:133], v[200:201], v[150:151]
	v_pk_fma_f32 v[148:149], v[136:137], v[202:203], v[148:149]
	v_pk_fma_f32 v[150:151], v[134:135], v[202:203], v[150:151]
	v_pk_fma_f32 v[148:149], v[138:139], v[206:207], v[148:149]
	s_waitcnt lgkmcnt(2)
	v_pk_add_f32 v[240:241], v[240:241], v[242:243]
	s_waitcnt lgkmcnt(0)
	v_pk_add_f32 v[244:245], v[244:245], v[248:249]
	ds_bpermute_b32 v242, v227, v240
	ds_bpermute_b32 v243, v227, v241
	ds_bpermute_b32 v248, v227, v244
	ds_bpermute_b32 v249, v227, v245
	v_pk_fma_f32 v[150:151], v[136:137], v[206:207], v[150:151]
	v_pk_fma_f32 v[148:149], v[140:141], v[208:209], v[148:149]
	v_pk_fma_f32 v[150:151], v[138:139], v[208:209], v[150:151]
	v_pk_fma_f32 v[148:149], v[142:143], v[212:213], v[148:149]
	v_pk_fma_f32 v[150:151], v[140:141], v[212:213], v[150:151]
	s_nop 0
	v_pk_fma_f32 v[150:151], v[142:143], v[210:211], v[150:151]
	s_waitcnt lgkmcnt(2)
	v_pk_add_f32 v[240:241], v[240:241], v[242:243]
	s_waitcnt lgkmcnt(0)
	v_pk_add_f32 v[244:245], v[244:245], v[248:249]
	s_and_saveexec_b64 s[6:7], s[4:5]
	ds_write_b64 v228, v[240:241] offset:63504
	ds_write_b64 v228, v[244:245] offset:63512
	s_or_b64 exec, exec, s[6:7]
	s_nop 0
	v_pk_mul_f32 v[250:251], v[148:149], v[148:149]
	v_pk_mul_f32 v[252:253], v[150:151], v[150:151]
	v_add_f32_e32 v240, v148, v149
	v_add_f32_e32 v244, v150, v151
	v_add_f32_e32 v241, v250, v251
	v_add_f32_e32 v245, v252, v253
	ds_bpermute_b32 v242, v222, v240
	ds_bpermute_b32 v243, v222, v241
	ds_bpermute_b32 v248, v222, v244
	ds_bpermute_b32 v249, v222, v245
	v_pk_fma_f32 v[152:153], v[122:123], v[152:153], v[128:129]
	v_lshlrev_b32_e32 v214, 16, v204
	v_pk_fma_f32 v[152:153], v[124:125], v[4:5], v[152:153]
	v_pk_fma_f32 v[4:5], v[122:123], v[4:5], v[128:129]
	v_and_b32_e32 v215, 0xffff0000, v204
	v_pk_fma_f32 v[152:153], v[126:127], v[6:7], v[152:153]
	v_lshlrev_b32_e32 v204, 16, v205
	v_pk_fma_f32 v[4:5], v[124:125], v[6:7], v[4:5]
	v_pk_fma_f32 v[152:153], v[120:121], v[8:9], v[152:153]
	v_and_b32_e32 v205, 0xffff0000, v205
	v_pk_fma_f32 v[4:5], v[126:127], v[8:9], v[4:5]
	v_pk_fma_f32 v[152:153], v[80:81], v[154:155], v[152:153]
	s_waitcnt lgkmcnt(2)
	v_pk_add_f32 v[240:241], v[240:241], v[242:243]
	s_waitcnt lgkmcnt(0)
	v_pk_add_f32 v[244:245], v[244:245], v[248:249]
	ds_bpermute_b32 v242, v223, v240
	ds_bpermute_b32 v243, v223, v241
	ds_bpermute_b32 v248, v223, v244
	ds_bpermute_b32 v249, v223, v245
	v_pk_fma_f32 v[4:5], v[120:121], v[154:155], v[4:5]
	v_pk_fma_f32 v[152:153], v[82:83], v[160:161], v[152:153]
	v_pk_fma_f32 v[4:5], v[80:81], v[160:161], v[4:5]
	v_pk_fma_f32 v[152:153], v[84:85], v[162:163], v[152:153]
	v_pk_fma_f32 v[4:5], v[82:83], v[162:163], v[4:5]
	v_pk_fma_f32 v[152:153], v[86:87], v[166:167], v[152:153]
	v_pk_fma_f32 v[4:5], v[84:85], v[166:167], v[4:5]
	v_pk_fma_f32 v[152:153], v[88:89], v[168:169], v[152:153]
	v_pk_fma_f32 v[4:5], v[86:87], v[168:169], v[4:5]
	v_pk_fma_f32 v[152:153], v[90:91], v[170:171], v[152:153]
	v_pk_fma_f32 v[4:5], v[88:89], v[170:171], v[4:5]
	v_pk_fma_f32 v[152:153], v[92:93], v[172:173], v[152:153]
	s_waitcnt lgkmcnt(2)
	v_pk_add_f32 v[240:241], v[240:241], v[242:243]
	s_waitcnt lgkmcnt(0)
	v_pk_add_f32 v[244:245], v[244:245], v[248:249]
	ds_bpermute_b32 v242, v224, v240
	ds_bpermute_b32 v243, v224, v241
	ds_bpermute_b32 v248, v224, v244
	ds_bpermute_b32 v249, v224, v245
	v_pk_fma_f32 v[4:5], v[90:91], v[172:173], v[4:5]
	v_pk_fma_f32 v[152:153], v[94:95], v[174:175], v[152:153]
	v_pk_fma_f32 v[4:5], v[92:93], v[174:175], v[4:5]
	v_pk_fma_f32 v[152:153], v[96:97], v[176:177], v[152:153]
	v_pk_fma_f32 v[4:5], v[94:95], v[176:177], v[4:5]
	v_pk_fma_f32 v[152:153], v[98:99], v[178:179], v[152:153]
	v_pk_fma_f32 v[4:5], v[96:97], v[178:179], v[4:5]
	v_pk_fma_f32 v[152:153], v[100:101], v[180:181], v[152:153]
	v_pk_fma_f32 v[4:5], v[98:99], v[180:181], v[4:5]
	v_pk_fma_f32 v[152:153], v[102:103], v[182:183], v[152:153]
	v_pk_fma_f32 v[4:5], v[100:101], v[182:183], v[4:5]
	v_pk_fma_f32 v[152:153], v[104:105], v[184:185], v[152:153]
	s_waitcnt lgkmcnt(2)
; DI void conv_item(const Params& p, char* lds, int t0, int tid) {
;     ...
;     for (int i = 0; i < 8; ++i) {
;       float a = bias.x, b = bias.y;
; #pragma unroll
;       for (int j = 0; j < 31; ++j) { a += wa[j] * za[i + j]; b += wb[j] * zb[i + j]; }
;       ya[i] = a; yb[i] = b;
;     }
; #pragma unroll
;     for (int i = 0; i < 8; ++i) {
;       float s1 = wave_sum(ya[i] + yb[i]);
;       float s2 = wave_sum(ya[i] * ya[i] + yb[i] * yb[i]);
;       if (lane == 0) { red[(w * 8 + i) * 2] = s1; red[(w * 8 + i) * 2 + 1] = s2; }
;     }
	v_pk_add_f32 v[240:241], v[240:241], v[242:243]
	s_waitcnt lgkmcnt(0)
	v_pk_add_f32 v[244:245], v[244:245], v[248:249]
	ds_bpermute_b32 v242, v225, v240
	ds_bpermute_b32 v243, v225, v241
	ds_bpermute_b32 v248, v225, v244
	ds_bpermute_b32 v249, v225, v245
	v_pk_fma_f32 v[4:5], v[102:103], v[184:185], v[4:5]
	v_pk_fma_f32 v[152:153], v[106:107], v[186:187], v[152:153]
	v_pk_fma_f32 v[4:5], v[104:105], v[186:187], v[4:5]
	v_pk_fma_f32 v[152:153], v[108:109], v[188:189], v[152:153]
	v_pk_fma_f32 v[4:5], v[106:107], v[188:189], v[4:5]
	v_pk_fma_f32 v[152:153], v[110:111], v[190:191], v[152:153]
	v_pk_fma_f32 v[4:5], v[108:109], v[190:191], v[4:5]
	v_pk_fma_f32 v[152:153], v[112:113], v[192:193], v[152:153]
	v_pk_fma_f32 v[4:5], v[110:111], v[192:193], v[4:5]
	v_pk_fma_f32 v[152:153], v[114:115], v[194:195], v[152:153]
	v_pk_fma_f32 v[4:5], v[112:113], v[194:195], v[4:5]
	v_pk_fma_f32 v[152:153], v[116:117], v[196:197], v[152:153]
	s_waitcnt lgkmcnt(2)
	v_pk_add_f32 v[240:241], v[240:241], v[242:243]
	s_waitcnt lgkmcnt(0)
	v_pk_add_f32 v[244:245], v[244:245], v[248:249]
	ds_bpermute_b32 v242, v226, v240
	ds_bpermute_b32 v243, v226, v241
	ds_bpermute_b32 v248, v226, v244
	ds_bpermute_b32 v249, v226, v245
	v_pk_fma_f32 v[4:5], v[114:115], v[196:197], v[4:5]
	v_pk_fma_f32 v[152:153], v[118:119], v[198:199], v[152:153]
	v_pk_fma_f32 v[4:5], v[116:117], v[198:199], v[4:5]
	v_pk_fma_f32 v[152:153], v[130:131], v[200:201], v[152:153]
	v_pk_fma_f32 v[4:5], v[118:119], v[200:201], v[4:5]
	v_pk_fma_f32 v[152:153], v[132:133], v[202:203], v[152:153]
	v_pk_fma_f32 v[4:5], v[130:131], v[202:203], v[4:5]
	v_pk_fma_f32 v[152:153], v[134:135], v[206:207], v[152:153]
	v_pk_fma_f32 v[4:5], v[132:133], v[206:207], v[4:5]
	v_pk_fma_f32 v[152:153], v[136:137], v[208:209], v[152:153]
	v_pk_fma_f32 v[4:5], v[134:135], v[208:209], v[4:5]
	v_pk_fma_f32 v[152:153], v[138:139], v[212:213], v[152:153]
	s_waitcnt lgkmcnt(2)
	v_pk_add_f32 v[240:241], v[240:241], v[242:243]
	s_waitcnt lgkmcnt(0)
	v_pk_add_f32 v[244:245], v[244:245], v[248:249]
	ds_bpermute_b32 v242, v227, v240
	ds_bpermute_b32 v243, v227, v241
	ds_bpermute_b32 v248, v227, v244
	ds_bpermute_b32 v249, v227, v245
	v_pk_fma_f32 v[4:5], v[136:137], v[212:213], v[4:5]
	v_pk_fma_f32 v[152:153], v[140:141], v[210:211], v[152:153]
	v_pk_fma_f32 v[4:5], v[138:139], v[210:211], v[4:5]
	v_pk_fma_f32 v[152:153], v[142:143], v[214:215], v[152:153]
	v_pk_fma_f32 v[4:5], v[140:141], v[214:215], v[4:5]
	s_nop 0
	v_pk_fma_f32 v[154:155], v[142:143], v[204:205], v[4:5]
	s_waitcnt lgkmcnt(2)
	v_pk_add_f32 v[240:241], v[240:241], v[242:243]
	s_waitcnt lgkmcnt(0)
	v_pk_add_f32 v[244:245], v[244:245], v[248:249]
	s_and_saveexec_b64 s[6:7], s[4:5]
	ds_write_b64 v228, v[240:241] offset:63520
	ds_write_b64 v228, v[244:245] offset:63528
	s_or_b64 exec, exec, s[6:7]
	s_nop 0
	v_pk_mul_f32 v[250:251], v[152:153], v[152:153]
	v_pk_mul_f32 v[252:253], v[154:155], v[154:155]
	v_add_f32_e32 v240, v152, v153
	v_add_f32_e32 v244, v154, v155
	v_add_f32_e32 v241, v250, v251
	v_add_f32_e32 v245, v252, v253
	ds_bpermute_b32 v242, v222, v240
	ds_bpermute_b32 v243, v222, v241
	ds_bpermute_b32 v248, v222, v244
	ds_bpermute_b32 v249, v222, v245
	s_waitcnt lgkmcnt(2)
	v_pk_add_f32 v[240:241], v[240:241], v[242:243]
	s_waitcnt lgkmcnt(0)
	v_pk_add_f32 v[244:245], v[244:245], v[248:249]
	ds_bpermute_b32 v242, v223, v240
	ds_bpermute_b32 v243, v223, v241
	ds_bpermute_b32 v248, v223, v244
	ds_bpermute_b32 v249, v223, v245
	s_waitcnt lgkmcnt(2)
	v_pk_add_f32 v[240:241], v[240:241], v[242:243]
	s_waitcnt lgkmcnt(0)
	v_pk_add_f32 v[244:245], v[244:245], v[248:249]
	ds_bpermute_b32 v242, v224, v240
	ds_bpermute_b32 v243, v224, v241
	ds_bpermute_b32 v248, v224, v244
	ds_bpermute_b32 v249, v224, v245
	s_waitcnt lgkmcnt(2)
	v_pk_add_f32 v[240:241], v[240:241], v[242:243]
	s_waitcnt lgkmcnt(0)
	v_pk_add_f32 v[244:245], v[244:245], v[248:249]
	ds_bpermute_b32 v242, v225, v240
	ds_bpermute_b32 v243, v225, v241
	ds_bpermute_b32 v248, v225, v244
	ds_bpermute_b32 v249, v225, v245
	s_waitcnt lgkmcnt(2)
	v_pk_add_f32 v[240:241], v[240:241], v[242:243]
	s_waitcnt lgkmcnt(0)
	v_pk_add_f32 v[244:245], v[244:245], v[248:249]
	ds_bpermute_b32 v242, v226, v240
	ds_bpermute_b32 v243, v226, v241
	ds_bpermute_b32 v248, v226, v244
	ds_bpermute_b32 v249, v226, v245
	s_waitcnt lgkmcnt(2)
	v_pk_add_f32 v[240:241], v[240:241], v[242:243]
	s_waitcnt lgkmcnt(0)
	v_pk_add_f32 v[244:245], v[244:245], v[248:249]
	ds_bpermute_b32 v242, v227, v240
	ds_bpermute_b32 v243, v227, v241
	ds_bpermute_b32 v248, v227, v244
	ds_bpermute_b32 v249, v227, v245
	s_waitcnt lgkmcnt(2)
	v_pk_add_f32 v[240:241], v[240:241], v[242:243]
	s_waitcnt lgkmcnt(0)
	v_pk_add_f32 v[244:245], v[244:245], v[248:249]
	s_and_saveexec_b64 s[6:7], s[4:5]
	ds_write_b64 v228, v[240:241] offset:63536
	ds_write_b64 v228, v[244:245] offset:63544
	s_branch .LBB0_195
